# out_gemm context-row tile epilogue: 16 serialized load-drain-fmac-store steps batched (17 loads in flight, one wait)
# speedup vs baseline: 1.2691x; 1.0035x over previous
; #define XCD_FOR(u, T)                                                                                         \
;   for (int _x = bid_() & 7, _gb = gridDim.x >> 3, _hi = (int)(((long)(_x + 1) * (T)) >> 3),                    \
;            u = (int)(((long)_x * (T)) >> 3) + (bid_() >> 3);                                                  \
;        u < _hi; u += _gb)
; template <int NT, bool BKN, bool MASK = false, bool ROWSS = false, class Epi> ...
;     ...
;   for (int kt = 0; kt < nk - 2; kt += 2) {
;     GEMM_COMPUTE(0);
;     GEMM_STORE(ra1, rb1, 1);
;     GEMM_LOAD(ra1, rb1, kt + 3);
;     __syncthreads();
;     GEMM_COMPUTE(1);
;     GEMM_STORE(ra0, rb0, 0);
;     GEMM_LOAD(ra0, rb0, (kt + 4 < nkm1 ? kt + 4 : nkm1));
;     __syncthreads();
;   }
;   GEMM_COMPUTE(0);
;   GEMM_STORE(ra1, rb1, 1);
;   __syncthreads();
;   GEMM_COMPUTE(1);
; __device__ __forceinline__ void phase_out_gemm(const Params& p, int l, bool last, const float* slat, const float* sctx, float* dlat, float* dctx, unsigned char* smem) {
;     ...
;     XCD_FOR(t, 4 * 32) {
;       const int mt = t >> 5, nt = t & 31, row_base = mt * 128;
;       const float* g1 = p.mada + (size_t)(l * 3 + 2) * 6144 + 2 * 1024 + nt * 32;
;       const float* xs = sctx + (size_t)row_base * DM;
;       float* xd = dctx + (size_t)row_base * DM;
;       auto epi = [&](f32x4(&acc)[4][1], int r0, int c0) {
; #pragma unroll
;         for (int mi = 0; mi < 4; ++mi) {
;           const float g = g1[c0];
; #pragma unroll
;           for (int j = 0; j < 4; ++j) {
;             const size_t o = (size_t)(r0 + mi * 16 + j) * DM + nt * 32 + c0;
;             xd[o] = xs[o] + g * acc[mi][0][j];
;           }
;         }
;       };
;       gemm_tile<1, false>(p.YM + (size_t)(T_LAT + row_base) * 1024, 1024, nullptr, 128, W + (size_t)nt * 32 * 1024, 1024, 1024, smem, epi);
.LBB0_855:
	ds_read_b128 v[86:89], v83
	ds_read_b128 v[90:93], v83 offset:2048
	ds_read_b128 v[94:97], v83 offset:4096
	ds_read_b128 v[98:101], v83 offset:6144
	ds_read_b128 v[102:105], v84 offset:16384
	s_add_i32 s0, s0, 2
	s_min_u32 s1, s0, 11
	s_lshl_b32 s94, s1, 7
	s_cmp_lt_u32 s0, 12
	s_waitcnt lgkmcnt(0)
	v_mfma_f32_16x16x32_bf16 v[42:45], v[86:89], v[102:105], v[42:45]
	v_mfma_f32_16x16x32_bf16 v[46:49], v[90:93], v[102:105], v[46:49]
	v_mfma_f32_16x16x32_bf16 v[50:53], v[94:97], v[102:105], v[50:53]
	v_mfma_f32_16x16x32_bf16 v[54:57], v[98:101], v[102:105], v[54:57]
	ds_read_b128 v[86:89], v81
	ds_read_b128 v[90:93], v81 offset:2048
	ds_read_b128 v[94:97], v81 offset:4096
	ds_read_b128 v[98:101], v81 offset:6144
	ds_read_b128 v[102:105], v82 offset:16384
	ds_write_b128 v80, v[2:5] offset:32768
	ds_write_b128 v80, v[6:9] offset:36864
	ds_write_b128 v80, v[10:13] offset:40960
	ds_write_b128 v80, v[14:17] offset:45056
	ds_write_b128 v80, v[18:21] offset:49152
	v_lshl_add_u64 v[14:15], v[74:75], 0, v[0:1]
	v_add_co_u32_e32 v6, vcc, s15, v14
	global_load_dwordx4 v[2:5], v[14:15], off offset:384
	s_nop 0
	v_addc_co_u32_e32 v7, vcc, 0, v15, vcc
	v_add_co_u32_e32 v10, vcc, s16, v14
	v_lshl_add_u64 v[18:19], v[72:73], 0, v[0:1]
	s_nop 0
	v_addc_co_u32_e32 v11, vcc, 0, v15, vcc
	v_add_co_u32_e32 v14, vcc, s17, v14
	s_waitcnt lgkmcnt(0)
	v_mfma_f32_16x16x32_bf16 v[42:45], v[86:89], v[102:105], v[42:45]
	v_addc_co_u32_e32 v15, vcc, 0, v15, vcc
	global_load_dwordx4 v[6:9], v[6:7], off offset:384
	v_mfma_f32_16x16x32_bf16 v[46:49], v[90:93], v[102:105], v[46:49]
	global_load_dwordx4 v[10:13], v[10:11], off offset:384
	v_lshl_add_u64 v[72:73], v[72:73], 0, s[6:7]
	global_load_dwordx4 v[14:17], v[14:15], off offset:384
	v_mfma_f32_16x16x32_bf16 v[50:53], v[94:97], v[102:105], v[50:53]
	global_load_dwordx4 v[18:21], v[18:19], off
	s_waitcnt lgkmcnt(0)
	s_barrier
	v_mfma_f32_16x16x32_bf16 v[54:57], v[98:101], v[102:105], v[54:57]
	ds_read_b128 v[86:89], v83 offset:32768
	ds_read_b128 v[90:93], v83 offset:34816
	ds_read_b128 v[94:97], v83 offset:36864
	ds_read_b128 v[98:101], v83 offset:38912
	ds_read_b128 v[102:105], v84 offset:49152
	v_lshl_add_u64 v[74:75], v[74:75], 0, s[6:7]
	s_waitcnt lgkmcnt(0)
	v_mfma_f32_16x16x32_bf16 v[42:45], v[86:89], v[102:105], v[42:45]
	v_mfma_f32_16x16x32_bf16 v[46:49], v[90:93], v[102:105], v[46:49]
	v_mfma_f32_16x16x32_bf16 v[50:53], v[94:97], v[102:105], v[50:53]
	v_mfma_f32_16x16x32_bf16 v[54:57], v[98:101], v[102:105], v[54:57]
	ds_read_b128 v[86:89], v81 offset:32768
	ds_read_b128 v[90:93], v81 offset:34816
	ds_read_b128 v[94:97], v81 offset:36864
	ds_read_b128 v[98:101], v81 offset:38912
	ds_read_b128 v[102:105], v82 offset:49152
	s_waitcnt vmcnt(0)
	ds_write_b128 v80, v[22:25]
	ds_write_b128 v80, v[26:29] offset:4096
	ds_write_b128 v80, v[30:33] offset:8192
	ds_write_b128 v80, v[34:37] offset:12288
	ds_write_b128 v80, v[38:41] offset:16384
	v_lshl_add_u64 v[22:23], v[62:63], 0, s[94:95]
	v_lshl_add_u64 v[26:27], v[64:65], 0, s[94:95]
	v_lshl_add_u64 v[30:31], v[66:67], 0, s[94:95]
	v_lshl_add_u64 v[34:35], v[68:69], 0, s[94:95]
	v_lshl_add_u64 v[38:39], v[70:71], 0, s[94:95]
	global_load_dwordx4 v[22:25], v[22:23], off offset:512
	s_waitcnt lgkmcnt(0)
	v_mfma_f32_16x16x32_bf16 v[42:45], v[86:89], v[102:105], v[42:45]
	global_load_dwordx4 v[26:29], v[26:27], off offset:512
	s_nop 0
	global_load_dwordx4 v[30:33], v[30:31], off offset:512
	v_mfma_f32_16x16x32_bf16 v[46:49], v[90:93], v[102:105], v[46:49]
	global_load_dwordx4 v[34:37], v[34:35], off offset:512
	s_nop 0
	global_load_dwordx4 v[38:41], v[38:39], off offset:512
	v_mfma_f32_16x16x32_bf16 v[50:53], v[94:97], v[102:105], v[50:53]
	s_waitcnt lgkmcnt(0)
	s_barrier
	v_mfma_f32_16x16x32_bf16 v[54:57], v[98:101], v[102:105], v[54:57]
	s_cbranch_scc1 .LBB0_855
	s_lshl_b64 s[0:1], s[44:45], 12
	s_add_u32 s44, s40, s0
	s_waitcnt vmcnt(0)
	v_lshl_add_u64 v[22:23], s[42:43], 2, v[60:61]
	s_addc_u32 s45, s41, s1
	s_lshl_b32 s94, s37, 7
	v_lshl_add_u64 v[60:61], v[22:23], 0, s[94:95]
	ds_read_b128 v[22:25], v83
	ds_read_b128 v[26:29], v83 offset:2048
	ds_read_b128 v[30:33], v83 offset:4096
	ds_read_b128 v[34:37], v83 offset:6144
	ds_read_b128 v[38:41], v84 offset:16384
	v_lshlrev_b32_e32 v0, 6, v78
	s_waitcnt lgkmcnt(0)
	v_mfma_f32_16x16x32_bf16 v[22:25], v[22:25], v[38:41], v[42:45]
	s_mov_b32 s34, 0xe000
	s_add_u32 s0, s82, s0
	s_addc_u32 s1, s83, s1
	v_mfma_f32_16x16x32_bf16 v[26:29], v[26:29], v[38:41], v[46:49]
	s_add_i32 s9, s9, s3
	s_add_i32 s18, s18, s3
	v_mfma_f32_16x16x32_bf16 v[30:33], v[30:33], v[38:41], v[50:53]
	v_mfma_f32_16x16x32_bf16 v[34:37], v[34:37], v[38:41], v[54:57]
	ds_read_b128 v[38:41], v81
	ds_read_b128 v[42:45], v81 offset:2048
	ds_read_b128 v[46:49], v81 offset:4096
	ds_read_b128 v[50:53], v81 offset:6144
	ds_read_b128 v[54:57], v82 offset:16384
	ds_write_b128 v80, v[2:5] offset:32768
	ds_write_b128 v80, v[6:9] offset:36864
	ds_write_b128 v80, v[10:13] offset:40960
	ds_write_b128 v80, v[14:17] offset:45056
	ds_write_b128 v80, v[18:21] offset:49152
	s_waitcnt lgkmcnt(0)
	s_barrier
; __device__ __forceinline__ void phase_out_gemm(const Params& p, int l, bool last, const float* slat, const float* sctx, float* dlat, float* dctx, unsigned char* smem) {
;     ...
;       auto epi = [&](f32x4(&acc)[4][1], int r0, int c0) {
; #pragma unroll
;         for (int mi = 0; mi < 4; ++mi) {
;           const float g = g1[c0];
; #pragma unroll
;           for (int j = 0; j < 4; ++j) {
;             const size_t o = (size_t)(r0 + mi * 16 + j) * DM + nt * 32 + c0;
;             xd[o] = xs[o] + g * acc[mi][0][j];
;           }
;         }
;       };
;       gemm_tile<1, false>(p.YM + (size_t)(T_LAT + row_base) * 1024, 1024, nullptr, 128, W + (size_t)nt * 32 * 1024, 1024, 1024, smem, epi);
	ds_read_b128 v[2:5], v83 offset:32768
	ds_read_b128 v[6:9], v83 offset:34816
	ds_read_b128 v[10:13], v83 offset:36864
	ds_read_b128 v[14:17], v83 offset:38912
	ds_read_b128 v[18:21], v84 offset:49152
	v_mfma_f32_16x16x32_bf16 v[22:25], v[38:41], v[54:57], v[22:25]
	v_mfma_f32_16x16x32_bf16 v[26:29], v[42:45], v[54:57], v[26:29]
	v_mfma_f32_16x16x32_bf16 v[30:33], v[46:49], v[54:57], v[30:33]
	v_mfma_f32_16x16x32_bf16 v[34:37], v[50:53], v[54:57], v[34:37]
	s_waitcnt lgkmcnt(0)
	v_mfma_f32_16x16x32_bf16 v[2:5], v[2:5], v[18:21], v[22:25]
	v_mfma_f32_16x16x32_bf16 v[6:9], v[6:9], v[18:21], v[26:29]
	v_mfma_f32_16x16x32_bf16 v[22:25], v[10:13], v[18:21], v[30:33]
	v_mfma_f32_16x16x32_bf16 v[18:21], v[14:17], v[18:21], v[34:37]
	ds_read_b128 v[10:13], v81 offset:32768
	ds_read_b128 v[26:29], v81 offset:34816
	ds_read_b128 v[30:33], v81 offset:36864
	ds_read_b128 v[34:37], v81 offset:38912
	ds_read_b128 v[38:41], v82 offset:49152
	s_waitcnt lgkmcnt(0)
	v_mfma_f32_16x16x32_bf16 v[14:17], v[10:13], v[38:41], v[2:5]
	v_mfma_f32_16x16x32_bf16 v[2:5], v[34:37], v[38:41], v[18:21]
	s_nop 2
	v_lshl_or_b32 v18, v79, 2, v0
	v_lshlrev_b32_e32 v0, 2, v77
	v_lshl_or_b32 v0, v76, 6, v0
	v_mfma_f32_16x16x32_bf16 v[10:13], v[26:29], v[38:41], v[6:9]
	v_lshl_add_u64 v[20:21], v[60:61], 0, v[0:1]
	v_or_b32_e32 v0, s94, v0
	v_add_co_u32_e32 v20, vcc, s34, v20
	v_mfma_f32_16x16x32_bf16 v[6:9], v[30:33], v[38:41], v[22:25]
	s_nop 0
	v_addc_co_u32_e32 v21, vcc, 0, v21, vcc
	v_lshl_or_b32 v18, v18, 12, v0
	global_load_dword v19, v[20:21], off
	v_mov_b32_e32 v42, v18
	v_add_u32_e32 v43, 0x1000, v18
	v_add_u32_e32 v44, 0x2000, v18
	v_add_u32_e32 v45, 0x3000, v18
	v_add_u32_e32 v46, 0x10000, v18
	v_add_u32_e32 v47, 0x11000, v18
	v_add_u32_e32 v48, 0x12000, v18
	v_add_u32_e32 v49, 0x13000, v18
	v_add_u32_e32 v50, 0x20000, v18
	v_add_u32_e32 v51, 0x21000, v18
	v_add_u32_e32 v52, 0x22000, v18
	v_add_u32_e32 v53, 0x23000, v18
	v_add_u32_e32 v54, 0x30000, v18
	v_add_u32_e32 v55, 0x31000, v18
	v_add_u32_e32 v56, 0x32000, v18
	v_add_u32_e32 v57, 0x33000, v18
	global_load_dword v62, v42, s[44:45]
	global_load_dword v63, v43, s[44:45]
	global_load_dword v64, v44, s[44:45]
	global_load_dword v65, v45, s[44:45]
	global_load_dword v66, v46, s[44:45]
	global_load_dword v67, v47, s[44:45]
	global_load_dword v68, v48, s[44:45]
	global_load_dword v69, v49, s[44:45]
	global_load_dword v70, v50, s[44:45]
	global_load_dword v71, v51, s[44:45]
	global_load_dword v72, v52, s[44:45]
	global_load_dword v73, v53, s[44:45]
	global_load_dword v74, v54, s[44:45]
	global_load_dword v75, v55, s[44:45]
	global_load_dword v86, v56, s[44:45]
	global_load_dword v87, v57, s[44:45]
	s_waitcnt vmcnt(0)
	v_fmac_f32_e32 v62, v14, v19
	v_fmac_f32_e32 v63, v15, v19
	v_fmac_f32_e32 v64, v16, v19
	v_fmac_f32_e32 v65, v17, v19
	v_fmac_f32_e32 v66, v10, v19
	v_fmac_f32_e32 v67, v11, v19
	v_fmac_f32_e32 v68, v12, v19
	v_fmac_f32_e32 v69, v13, v19
	v_fmac_f32_e32 v70, v6, v19
	v_fmac_f32_e32 v71, v7, v19
	v_fmac_f32_e32 v72, v8, v19
	v_fmac_f32_e32 v73, v9, v19
	v_fmac_f32_e32 v74, v2, v19
	v_fmac_f32_e32 v75, v3, v19
	v_fmac_f32_e32 v86, v4, v19
	v_fmac_f32_e32 v87, v5, v19
	global_store_dword v42, v62, s[0:1]
	global_store_dword v43, v63, s[0:1]
	global_store_dword v44, v64, s[0:1]
	global_store_dword v45, v65, s[0:1]
	global_store_dword v46, v66, s[0:1]
	global_store_dword v47, v67, s[0:1]
	global_store_dword v48, v68, s[0:1]
	global_store_dword v49, v69, s[0:1]
	global_store_dword v50, v70, s[0:1]
	global_store_dword v51, v71, s[0:1]
	global_store_dword v52, v72, s[0:1]
	global_store_dword v53, v73, s[0:1]
	global_store_dword v54, v74, s[0:1]
	global_store_dword v55, v75, s[0:1]
	global_store_dword v56, v86, s[0:1]
	global_store_dword v57, v87, s[0:1]
	v_readlane_b32 s0, v254, 51
	s_add_i32 s19, s19, s0
	s_cmp_lt_i32 s9, s8
	s_cbranch_scc1 .LBB0_854
